# v14 plus prompt queue de-synchronisation: ids of adjacent query-block size classes interleaved in blocks of 64 so workgroups stop dequeuing in lockstep
# speedup vs baseline: 1.0157x; 1.0157x over previous
.LBB0_875:
	s_andn2_b64 vcc, exec, s[8:9]
	s_cbranch_vccnz .LBB0_877
	s_lshr_b32 s99, s10, 6
	s_lshr_b32 s98, s10, 7
	s_xor_b32 s99, s99, s98
	s_and_b32 s99, s99, 1
	s_mul_i32 s99, s99, 0xc0
	s_xor_b32 s10, s10, s99
	s_ashr_i32 s8, s10, 7
	s_sub_i32 s16, 7, s8
	s_lshl_b32 s8, s10, 8
	s_and_b32 s14, s8, 0x7800
	s_and_b32 s8, s10, 0x78
	s_add_i32 s8, s16, s8
	s_and_b32 s15, s10, 7
	s_lshl_b32 s8, s8, 8
	s_branch .LBB0_878

.LBB0_1076:
	s_ashr_i32 s29, s28, 31
	s_lshl_b64 s[30:31], s[28:29], 19
	s_add_u32 s30, s3, s30
	s_addc_u32 s31, s45, s31
	s_and_b64 s[40:41], s[6:7], exec
	s_cselect_b32 s29, s31, s53
	s_cselect_b32 s65, s30, s52
	s_ashr_i32 s27, s26, 31
	s_lshl_b64 s[40:41], s[26:27], 19
	s_add_u32 s40, s62, s40
	s_addc_u32 s41, s63, s41
	s_and_b64 s[46:47], s[6:7], exec
	s_cselect_b32 s27, s41, s55
	s_cselect_b32 s66, s40, s54
	s_add_u32 s52, s52, 0x40080
	s_addc_u32 s53, s53, 0
	s_add_u32 s67, s54, 0x100
	v_mov_b32_e32 v0, 0
	s_addc_u32 s68, s55, 0
	s_mov_b32 s69, -2
	v_mov_b32_e32 v1, v0
	v_mov_b32_e32 v2, v0
	v_mov_b32_e32 v3, v0
	v_mov_b32_e32 v4, v0
	v_mov_b32_e32 v5, v0
	v_mov_b32_e32 v6, v0
	v_mov_b32_e32 v7, v0
	v_mov_b32_e32 v16, v0
	v_mov_b32_e32 v17, v0
	v_mov_b32_e32 v18, v0
	v_mov_b32_e32 v19, v0
	v_mov_b32_e32 v20, v0
	v_mov_b32_e32 v21, v0
	v_mov_b32_e32 v22, v0
	v_mov_b32_e32 v23, v0
	v_mov_b32_e32 v32, v0
	v_mov_b32_e32 v33, v0
	v_mov_b32_e32 v34, v0
	v_mov_b32_e32 v35, v0
	v_mov_b32_e32 v36, v0
	v_mov_b32_e32 v37, v0
	v_mov_b32_e32 v38, v0
	v_mov_b32_e32 v39, v0
	v_mov_b32_e32 v48, v0
	v_mov_b32_e32 v49, v0
	v_mov_b32_e32 v50, v0
	v_mov_b32_e32 v51, v0
	v_mov_b32_e32 v52, v0
	v_mov_b32_e32 v53, v0
	v_mov_b32_e32 v54, v0
	v_mov_b32_e32 v55, v0
	v_mov_b32_e32 v8, v0
	v_mov_b32_e32 v9, v0
	v_mov_b32_e32 v10, v0
	v_mov_b32_e32 v11, v0
	v_mov_b32_e32 v12, v0
	v_mov_b32_e32 v13, v0
	v_mov_b32_e32 v14, v0
	v_mov_b32_e32 v15, v0
	v_mov_b32_e32 v24, v0
	v_mov_b32_e32 v25, v0
	v_mov_b32_e32 v26, v0
	v_mov_b32_e32 v27, v0
	v_mov_b32_e32 v28, v0
	v_mov_b32_e32 v29, v0
	v_mov_b32_e32 v30, v0
	v_mov_b32_e32 v31, v0
	v_mov_b32_e32 v40, v0
	v_mov_b32_e32 v41, v0
	v_mov_b32_e32 v42, v0
	v_mov_b32_e32 v43, v0
	v_mov_b32_e32 v44, v0
	v_mov_b32_e32 v45, v0
	v_mov_b32_e32 v46, v0
	v_mov_b32_e32 v47, v0
	v_mov_b32_e32 v56, v0
	v_mov_b32_e32 v57, v0
	v_mov_b32_e32 v58, v0
	v_mov_b32_e32 v59, v0
	v_mov_b32_e32 v60, v0
	v_mov_b32_e32 v61, v0
	v_mov_b32_e32 v62, v0
	v_mov_b32_e32 v63, v0
	v_mov_b32_e32 v64, v0
	v_mov_b32_e32 v65, v0
	v_mov_b32_e32 v66, v0
	v_mov_b32_e32 v67, v0
	v_mov_b32_e32 v68, v0
	v_mov_b32_e32 v69, v0
	v_mov_b32_e32 v70, v0
	v_mov_b32_e32 v71, v0
	v_mov_b32_e32 v80, v0
	v_mov_b32_e32 v81, v0
	v_mov_b32_e32 v82, v0
	v_mov_b32_e32 v83, v0
	v_mov_b32_e32 v84, v0
	v_mov_b32_e32 v85, v0
	v_mov_b32_e32 v86, v0
	v_mov_b32_e32 v87, v0
	v_mov_b32_e32 v96, v0
	v_mov_b32_e32 v97, v0
	v_mov_b32_e32 v98, v0
	v_mov_b32_e32 v99, v0
	v_mov_b32_e32 v100, v0
	v_mov_b32_e32 v101, v0
	v_mov_b32_e32 v102, v0
	v_mov_b32_e32 v103, v0
	v_mov_b32_e32 v112, v0
	v_mov_b32_e32 v113, v0
	v_mov_b32_e32 v114, v0
	v_mov_b32_e32 v115, v0
	v_mov_b32_e32 v116, v0
	v_mov_b32_e32 v117, v0
	v_mov_b32_e32 v118, v0
	v_mov_b32_e32 v119, v0
	v_mov_b32_e32 v72, v0
	v_mov_b32_e32 v73, v0
	v_mov_b32_e32 v74, v0
	v_mov_b32_e32 v75, v0
	v_mov_b32_e32 v76, v0
	v_mov_b32_e32 v77, v0
	v_mov_b32_e32 v78, v0
	v_mov_b32_e32 v79, v0
	v_mov_b32_e32 v88, v0
	v_mov_b32_e32 v89, v0
	v_mov_b32_e32 v90, v0
	v_mov_b32_e32 v91, v0
	v_mov_b32_e32 v92, v0
	v_mov_b32_e32 v93, v0
	v_mov_b32_e32 v94, v0
	v_mov_b32_e32 v95, v0
	v_mov_b32_e32 v104, v0
	v_mov_b32_e32 v105, v0
	v_mov_b32_e32 v106, v0
	v_mov_b32_e32 v107, v0
	v_mov_b32_e32 v108, v0
	v_mov_b32_e32 v109, v0
	v_mov_b32_e32 v110, v0
	v_mov_b32_e32 v111, v0
	v_mov_b32_e32 v120, v0
	v_mov_b32_e32 v121, v0
	v_mov_b32_e32 v122, v0
	v_mov_b32_e32 v123, v0
	v_mov_b32_e32 v124, v0
	v_mov_b32_e32 v125, v0
	v_mov_b32_e32 v126, v0
	v_mov_b32_e32 v127, v0
	s_nop 0
	s_nop 0
	s_nop 0
	s_nop 0
	s_nop 0
	s_nop 0
	s_nop 0
	s_nop 0
	s_nop 0
	s_nop 0
	s_nop 0
